# rwkv scan units remapped so the four row-group workgroups of one (batch,head) sit on the same XCD (shared L2 for the scan feed)
# speedup vs baseline: 1.0748x; 1.0037x over previous
.LBB0_457:
	s_cmp_gt_i32 s82, 5
	v_and_b32_e32 v161, 63, v166
	s_cbranch_scc1 .LBB0_519
	v_writelane_b32 v255, s0, 39
	s_mov_b32 s96, s88
	s_nop 0
	v_writelane_b32 v255, s1, 40
	v_readlane_b32 s0, v250, 34
	v_readlane_b32 s1, v250, 35
	s_andn2_b64 vcc, exec, s[0:1]
	s_cbranch_vccnz .LBB0_512
	v_lshlrev_b32_e32 v0, 4, v161
	v_readlane_b32 s0, v255, 35
	v_and_b32_e32 v170, 0xf0, v0
	v_mov_b32_e32 v171, v1
	v_readlane_b32 s1, v255, 36
	v_and_b32_e32 v0, 0x1f0, v0
	v_and_b32_e32 v2, 1, v166
	v_lshl_add_u64 v[172:173], s[0:1], 0, v[170:171]
	v_readlane_b32 s0, v255, 33
	v_readlane_b32 s1, v255, 34
	v_lshlrev_b32_e32 v187, 5, v2
	v_lshrrev_b32_e32 v191, 5, v161
	v_lshl_add_u64 v[174:175], s[0:1], 0, v[0:1]
	v_lshlrev_b32_e32 v0, 3, v2
	v_or_b32_e32 v2, 64, v161
	v_lshrrev_b32_e32 v188, 4, v2
	v_lshrrev_b32_e32 v192, 5, v2
	s_movk_i32 s0, 0x500
	v_mov_b32_e32 v2, 0x2800
	v_mad_u32_u24 v229, v191, s0, v2
	v_mov_b32_e32 v2, 0x3200
	v_lshlrev_b32_e32 v3, 5, v161
	v_mad_u32_u24 v230, v191, s0, v2
	v_mov_b32_e32 v2, 0x3c00
	v_lshrrev_b32_e32 v167, 4, v161
	v_and_b32_e32 v185, 0x3e0, v3
	v_and_b32_e32 v186, 0x3c0, v3
	v_or_b32_e32 v3, 0x80, v161
	v_or_b32_e32 v4, 0xc0, v161
	v_mad_u32_u24 v231, v191, s0, v2
	v_mov_b32_e32 v2, 0x4600
	s_cmp_lt_i32 s82, 4
	v_lshl_or_b32 v169, s82, 2, v167
	v_and_b32_e32 v182, 15, v166
	v_lshrrev_b32_e32 v189, 4, v3
	v_lshrrev_b32_e32 v190, 4, v4
	v_lshrrev_b32_e32 v193, 5, v3
	v_lshrrev_b32_e32 v194, 5, v4
	v_mad_u32_u24 v232, v191, s0, v2
	v_readlane_b32 s0, v255, 13
	s_cselect_b64 s[42:43], -1, 0
	v_lshlrev_b32_e32 v168, 2, v182
	v_lshlrev_b32_e32 v183, 4, v182
	v_lshlrev_b32_e32 v184, 2, v169
	s_mov_b32 s83, 0
	v_cmp_eq_u32_e64 s[38:39], 0, v161
	v_bfe_u32 v171, v166, 1, 4
	v_cmp_gt_u32_e64 s[44:45], 32, v161
	v_cmp_eq_u32_e64 s[8:9], 0, v182
	v_cmp_eq_u32_e64 s[10:11], 1, v182
	v_cmp_eq_u32_e64 s[18:19], 2, v182
	v_cmp_eq_u32_e64 s[6:7], 3, v182
	v_cmp_eq_u32_e64 s[80:81], 4, v182
	v_cmp_eq_u32_e64 s[90:91], 5, v182
	v_cmp_eq_u32_e64 s[74:75], 6, v182
	v_cmp_eq_u32_e64 s[56:57], 7, v182
	v_cmp_eq_u32_e64 s[58:59], 8, v182
	v_cmp_eq_u32_e64 s[60:61], 9, v182
	v_cmp_eq_u32_e64 s[62:63], 10, v182
	v_cmp_eq_u32_e64 s[64:65], 11, v182
	v_cmp_eq_u32_e64 s[66:67], 12, v182
	v_cmp_eq_u32_e64 s[68:69], 14, v182
	v_cmp_eq_u32_e64 s[70:71], 13, v182
	v_cmp_eq_u32_e64 s[72:73], 15, v182
	v_or_b32_e32 v195, 8, v191
	v_or_b32_e32 v196, 10, v191
	v_or_b32_e32 v197, 12, v191
	v_or_b32_e32 v198, 14, v191
	v_mul_u32_u24_e32 v199, 0x500, v167
	v_mul_u32_u24_e32 v200, 0x500, v188
	v_mul_u32_u24_e32 v201, 0x500, v189
	v_mul_u32_u24_e32 v224, 0x500, v190
	v_mul_u32_u24_e32 v225, 0x500, v191
	v_mul_u32_u24_e32 v226, 0x500, v192
	v_mul_u32_u24_e32 v227, 0x500, v193
	v_mul_u32_u24_e32 v228, 0x500, v194
	v_lshlrev_b32_e32 v0, 1, v0
	s_and_b32 s84, s0, 7
	s_lshl_b32 s84, s84, 5
	s_lshr_b32 s1, s0, 3
	s_add_i32 s84, s84, s1
	v_readlane_b32 s1, v255, 14
	s_branch .LBB0_462
